# speedup vs baseline: 1.0432x; 1.0065x over previous
.LBB0_138:
	ds_read_b128 v[80:83], v213 offset:49152
	ds_read_b128 v[84:87], v214 offset:49152
	ds_read_b128 v[222:225], v202 offset:53248
	ds_read_b128 v[226:229], v203 offset:53248
	ds_read_b128 v[230:233], v215 offset:49152
	ds_read_b128 v[234:237], v216 offset:49152
	ds_read_b128 v[238:241], v204 offset:53248
	ds_read_b128 v[242:245], v205 offset:53248
	s_waitcnt lgkmcnt(6)
	v_mfma_f32_32x32x64_f8f6f4 v[96:111], v[80:87], v[122:129], 0
	s_waitcnt lgkmcnt(4)
	v_mfma_f32_32x32x64_f8f6f4 v[80:95], v[222:229], v[122:129], 0
	s_waitcnt lgkmcnt(2)
	v_mfma_f32_32x32x64_f8f6f4 v[96:111], v[230:237], v[130:137], v[96:111]
	s_waitcnt lgkmcnt(0)
	v_mfma_f32_32x32x64_f8f6f4 v[80:95], v[238:245], v[130:137], v[80:95]
	v_exp_f32_e32 v139, v170
	v_exp_f32_e32 v162, v171
	v_exp_f32_e32 v158, v158
	v_exp_f32_e32 v159, v159
	v_exp_f32_e32 v154, v154
	v_exp_f32_e32 v155, v155
	v_exp_f32_e32 v142, v142
	v_exp_f32_e32 v143, v143
	v_exp_f32_e32 v160, v160
	v_exp_f32_e32 v161, v161
	v_exp_f32_e32 v156, v156
	v_exp_f32_e32 v157, v157
	v_exp_f32_e32 v144, v144
	v_exp_f32_e32 v145, v145
	v_exp_f32_e32 v140, v140
	v_exp_f32_e32 v141, v141
	v_cvt_pk_fp8_f32 v222, v219, v220
	v_cvt_pk_fp8_f32 v226, v139, v162
	v_cvt_pk_fp8_f32 v223, v185, v218
	v_cvt_pk_fp8_f32 v227, v158, v159
	v_cvt_pk_fp8_f32 v224, v180, v182
	v_cvt_pk_fp8_f32 v228, v154, v155
	v_cvt_pk_fp8_f32 v225, v177, v178
	v_cvt_pk_fp8_f32 v229, v142, v143
	v_cvt_pk_fp8_f32 v222, v179, v181 op_sel:[0,0,1]
	v_cvt_pk_fp8_f32 v226, v160, v161 op_sel:[0,0,1]
	v_cvt_pk_fp8_f32 v223, v183, v184 op_sel:[0,0,1]
	v_cvt_pk_fp8_f32 v227, v156, v157 op_sel:[0,0,1]
	v_cvt_pk_fp8_f32 v224, v173, v174 op_sel:[0,0,1]
	v_cvt_pk_fp8_f32 v228, v144, v145 op_sel:[0,0,1]
	v_cvt_pk_fp8_f32 v225, v175, v176 op_sel:[0,0,1]
	v_cvt_pk_fp8_f32 v229, v140, v141 op_sel:[0,0,1]
	s_add_i32 s4, s13, -1
	s_cmp_lt_i32 s4, s11
	s_cselect_b32 s5, 0, s11
	s_cselect_b32 s9, s91, s95
	s_cselect_b32 s8, s90, s94
	s_cselect_b32 s14, s92, s96
	s_cselect_b32 s15, s93, s97
	s_sub_i32 s20, s4, s5
	s_lshl_b64 s[4:5], s[20:21], 15
	s_add_u32 s8, s8, s4
	s_addc_u32 s9, s9, s5
	s_add_u32 s4, s14, s4
	s_addc_u32 s5, s15, s5
	v_lshl_add_u64 v[140:141], s[4:5], 0, v[166:167]
	global_load_dwordx4 v[158:161], v[140:141], off
	v_lshl_add_u64 v[140:141], s[8:9], 0, v[168:169]
	global_load_dwordx4 v[154:157], v[140:141], off
	v_add_u32_e32 v162, v210, v199
	v_add_u32_e32 v218, v210, v200
	ds_read_b128 v[174:177], v162
	ds_read_b128 v[230:233], v162 offset:2048
	ds_read_b128 v[178:181], v218
	ds_read_b128 v[234:237], v218 offset:2048
	ds_read_b128 v[238:241], v162 offset:4096
	ds_read_b128 v[246:249], v162 offset:6144
	ds_read_b128 v[242:245], v218 offset:4096
	ds_read_b128 v[250:253], v218 offset:6144
	s_waitcnt lgkmcnt(5)
	v_mfma_f32_32x32x64_f8f6f4 v[48:63], v[222:229], v[174:181], v[48:63]
	s_waitcnt lgkmcnt(4)
	v_mfma_f32_32x32x64_f8f6f4 v[32:47], v[222:229], v[230:237], v[32:47]
	s_waitcnt lgkmcnt(1)
	v_mfma_f32_32x32x64_f8f6f4 v[16:31], v[222:229], v[238:245], v[16:31]
	s_waitcnt lgkmcnt(0)
	v_mfma_f32_32x32x64_f8f6f4 v[0:15], v[222:229], v[246:253], v[0:15]
	v_mfma_f32_32x32x64_f8f6f4 v[64:79], v[222:229], v[114:121], v[64:79]
	v_max_f32_e32 v139, v97, v97
	v_max_f32_e32 v140, v96, v96
	v_max_f32_e32 v139, v140, v139
	v_max3_f32 v139, v139, v98, v99
	v_max3_f32 v139, v139, v100, v101
	v_max3_f32 v139, v139, v102, v103
	v_max3_f32 v139, v139, v104, v105
	v_max3_f32 v139, v139, v106, v107
	v_max3_f32 v139, v139, v108, v109
	v_max3_f32 v139, v139, v110, v111
	v_max3_f32 v139, v139, v80, v81
	v_max3_f32 v139, v139, v82, v83
	v_max3_f32 v139, v139, v84, v85
	v_max3_f32 v139, v139, v86, v87
	v_max3_f32 v139, v139, v88, v89
	v_max3_f32 v139, v139, v90, v91
	v_max3_f32 v139, v139, v92, v93
	v_max3_f32 v139, v139, v94, v95
	v_mov_b32_e32 v140, v139
	s_nop 1
	v_permlane32_swap_b32_e32 v139, v140
	v_max_f32_e32 v140, v140, v140
	v_max_f32_e32 v139, v139, v139
	v_max_f32_e32 v139, v139, v140
	v_sub_f32_e32 v140, v139, v172
	v_cmp_ge_f32_e32 vcc, s63, v140
	s_cmp_lg_u64 vcc, exec
	s_cselect_b64 s[8:9], -1, 0
	s_mov_b64 vcc, s[8:9]
	s_cbranch_vccnz .LBB0_156
	v_mov_b32_e32 v140, v138

.LBB0_147:
	v_exp_f32_e32 v170, v170
	v_exp_f32_e32 v171, v171
	v_exp_f32_e32 v174, v174
	v_exp_f32_e32 v175, v175
	v_exp_f32_e32 v178, v178
	v_exp_f32_e32 v179, v179
	v_exp_f32_e32 v182, v182
	v_exp_f32_e32 v183, v183
	v_cvt_pk_fp8_f32 v138, v235, v236
	v_exp_f32_e32 v172, v172
	v_exp_f32_e32 v173, v173
	v_exp_f32_e32 v176, v176
	v_exp_f32_e32 v177, v177
	v_exp_f32_e32 v184, v184
	v_exp_f32_e32 v185, v185
	v_exp_f32_e32 v180, v180
	v_exp_f32_e32 v181, v181
	v_cvt_pk_fp8_f32 v142, v170, v171
	v_cvt_pk_fp8_f32 v139, v233, v234
	v_cvt_pk_fp8_f32 v143, v174, v175
	v_cvt_pk_fp8_f32 v138, v227, v229 op_sel:[0,0,1]
	v_cvt_pk_fp8_f32 v140, v228, v230
	v_cvt_pk_fp8_f32 v144, v178, v179
	v_cvt_pk_fp8_f32 v141, v225, v226
	v_cvt_pk_fp8_f32 v145, v182, v183
	v_cvt_pk_fp8_f32 v142, v172, v173 op_sel:[0,0,1]
	v_cvt_pk_fp8_f32 v139, v231, v232 op_sel:[0,0,1]
	v_cvt_pk_fp8_f32 v143, v176, v177 op_sel:[0,0,1]
	v_cvt_pk_fp8_f32 v140, v221, v222 op_sel:[0,0,1]
	v_cvt_pk_fp8_f32 v144, v184, v185 op_sel:[0,0,1]
	v_cvt_pk_fp8_f32 v141, v223, v224 op_sel:[0,0,1]
	v_cvt_pk_fp8_f32 v145, v180, v181 op_sel:[0,0,1]
	ds_read_b128 v[170:173], v162 offset:16384
	ds_read_b128 v[178:181], v162 offset:18432
	ds_read_b128 v[174:177], v218 offset:16384
	ds_read_b128 v[182:185], v218 offset:18432
	ds_read_b128 v[222:225], v162 offset:20480
	ds_read_b128 v[230:233], v162 offset:22528
	ds_read_b128 v[226:229], v218 offset:20480
	ds_read_b128 v[234:237], v218 offset:22528
	s_waitcnt lgkmcnt(5)
	v_mfma_f32_32x32x64_f8f6f4 v[48:63], v[138:145], v[170:177], v[48:63]
	s_waitcnt lgkmcnt(4)
	v_mfma_f32_32x32x64_f8f6f4 v[32:47], v[138:145], v[178:185], v[32:47]
	s_waitcnt lgkmcnt(1)
	v_mfma_f32_32x32x64_f8f6f4 v[16:31], v[138:145], v[222:229], v[16:31]
	s_waitcnt lgkmcnt(0)
	v_mfma_f32_32x32x64_f8f6f4 v[0:15], v[138:145], v[230:237], v[0:15]
	v_mfma_f32_32x32x64_f8f6f4 v[64:79], v[138:145], v[114:121], v[64:79]
	v_max_f32_e32 v138, v97, v97
	v_max_f32_e32 v139, v96, v96
	v_max_f32_e32 v138, v139, v138
	v_max3_f32 v138, v138, v98, v99
	v_max3_f32 v138, v138, v100, v101
	v_max3_f32 v138, v138, v102, v103
	v_max3_f32 v138, v138, v104, v105
	v_max3_f32 v138, v138, v106, v107
	v_max3_f32 v138, v138, v108, v109
	v_max3_f32 v138, v138, v110, v111
	v_max3_f32 v138, v138, v80, v81
	v_max3_f32 v138, v138, v82, v83
	v_max3_f32 v138, v138, v84, v85
	v_max3_f32 v138, v138, v86, v87
	v_max3_f32 v138, v138, v88, v89
	v_max3_f32 v138, v138, v90, v91
	v_max3_f32 v138, v138, v92, v93
	v_max3_f32 v138, v138, v94, v95
	v_mov_b32_e32 v139, v138
	s_nop 1
	v_permlane32_swap_b32_e32 v138, v139
	v_max_f32_e32 v139, v139, v139
	v_max_f32_e32 v138, v138, v138
	v_max_f32_e32 v138, v138, v139
	v_sub_f32_e32 v139, v138, v219
	v_cmp_ge_f32_e32 vcc, s63, v139
	s_cmp_lg_u64 vcc, exec
	s_cselect_b64 s[8:9], -1, 0
	s_mov_b64 vcc, s[8:9]
	s_cbranch_vccnz .LBB0_157
	v_mov_b32_e32 v162, v220

.LBB0_193:
	s_add_i32 s4, s33, -1
	v_exp_f32_e32 v156, v156
	v_exp_f32_e32 v157, v157
	s_cmp_lt_i32 s4, s11
	v_exp_f32_e32 v160, v160
	v_exp_f32_e32 v161, v161
	s_cselect_b32 s5, 0, s11
	s_cselect_b32 s9, s91, s95
	s_cselect_b32 s8, s90, s94
	s_cselect_b32 s29, s92, s96
	s_cselect_b32 s34, s93, s97
	s_sub_i32 s20, s4, s5
	s_lshl_b64 s[4:5], s[20:21], 15
	v_exp_f32_e32 v154, v154
	v_exp_f32_e32 v155, v155
	v_cvt_pk_fp8_f32 v145, v156, v157
	s_add_u32 s8, s8, s4
	v_exp_f32_e32 v158, v158
	v_exp_f32_e32 v159, v159
	v_cvt_pk_fp8_f32 v144, v160, v161
	s_addc_u32 s9, s9, s5
	s_add_u32 s4, s29, s4
	s_addc_u32 s5, s34, s5
	v_cvt_pk_fp8_f32 v145, v154, v155 op_sel:[0,0,1]
	v_lshl_add_u64 v[154:155], s[4:5], 0, v[168:169]
	v_cvt_pk_fp8_f32 v144, v158, v159 op_sel:[0,0,1]
	global_load_dwordx4 v[158:161], v[154:155], off
	v_lshl_add_u64 v[154:155], s[8:9], 0, v[170:171]
	global_load_dwordx4 v[154:157], v[154:155], off
	v_exp_f32_e32 v178, v178
	v_exp_f32_e32 v179, v179
	v_exp_f32_e32 v174, v174
	v_exp_f32_e32 v175, v175
	v_cvt_pk_fp8_f32 v138, v228, v229
	v_exp_f32_e32 v176, v176
	v_exp_f32_e32 v177, v177
	v_exp_f32_e32 v172, v172
	v_exp_f32_e32 v173, v173
	v_cvt_pk_fp8_f32 v138, v221, v223 op_sel:[0,0,1]
	v_cvt_pk_fp8_f32 v142, v178, v179
	v_cvt_pk_fp8_f32 v139, v226, v227
	v_cvt_pk_fp8_f32 v143, v174, v175
	v_cvt_pk_fp8_f32 v140, v220, v222
	v_cvt_pk_fp8_f32 v141, v185, v219
	v_cvt_pk_fp8_f32 v142, v176, v177 op_sel:[0,0,1]
	v_cvt_pk_fp8_f32 v139, v224, v225 op_sel:[0,0,1]
	v_cvt_pk_fp8_f32 v143, v172, v173 op_sel:[0,0,1]
	v_cvt_pk_fp8_f32 v140, v181, v182 op_sel:[0,0,1]
	v_cvt_pk_fp8_f32 v141, v183, v184 op_sel:[0,0,1]
	ds_read_b128 v[172:175], v215
	ds_read_b128 v[220:223], v215 offset:2048
	ds_read_b128 v[176:179], v216
	ds_read_b128 v[224:227], v216 offset:2048
	ds_read_b128 v[228:231], v215 offset:4096
	ds_read_b128 v[236:239], v215 offset:6144
	ds_read_b128 v[232:235], v216 offset:4096
	ds_read_b128 v[240:243], v216 offset:6144
	s_waitcnt lgkmcnt(5)
	v_mfma_f32_32x32x64_f8f6f4 v[48:63], v[138:145], v[172:179], v[48:63]
	s_waitcnt lgkmcnt(4)
	v_mfma_f32_32x32x64_f8f6f4 v[32:47], v[138:145], v[220:227], v[32:47]
	s_waitcnt lgkmcnt(1)
	v_mfma_f32_32x32x64_f8f6f4 v[16:31], v[138:145], v[228:235], v[16:31]
	s_waitcnt lgkmcnt(0)
	v_mfma_f32_32x32x64_f8f6f4 v[0:15], v[138:145], v[236:243], v[0:15]
	v_mfma_f32_32x32x64_f8f6f4 v[64:79], v[138:145], v[114:121], v[64:79]
	v_max_f32_e32 v138, v97, v97
	v_max_f32_e32 v139, v96, v96
	v_max_f32_e32 v138, v139, v138
	v_max3_f32 v138, v138, v98, v99
	v_max3_f32 v138, v138, v100, v101
	v_max3_f32 v138, v138, v102, v103
	v_max3_f32 v138, v138, v104, v105
	v_max3_f32 v138, v138, v106, v107
	v_max3_f32 v138, v138, v108, v109
	v_max3_f32 v138, v138, v110, v111
	v_max3_f32 v138, v138, v80, v81
	v_max3_f32 v138, v138, v82, v83
	v_max3_f32 v138, v138, v84, v85
	v_max3_f32 v138, v138, v86, v87
	v_max3_f32 v138, v138, v88, v89
	v_max3_f32 v138, v138, v90, v91
	v_max3_f32 v138, v138, v92, v93
	v_max3_f32 v138, v138, v94, v95
	v_mov_b32_e32 v139, v138
	s_nop 1
	v_permlane32_swap_b32_e32 v138, v139
	v_max_f32_e32 v139, v139, v139
	v_max_f32_e32 v138, v138, v138
	v_max_f32_e32 v138, v138, v139
	v_sub_f32_e32 v139, v138, v180
	v_cmp_ge_f32_e32 vcc, s63, v139
	s_cmp_lg_u64 vcc, exec
	s_cselect_b64 s[8:9], -1, 0
	s_mov_b64 vcc, s[8:9]
	s_cbranch_vccnz .LBB0_214
	v_mov_b32_e32 v138, v166

.LBB0_205:
	v_exp_f32_e32 v166, v166
	v_exp_f32_e32 v167, v167
	v_exp_f32_e32 v174, v174
	v_exp_f32_e32 v175, v175
	v_exp_f32_e32 v178, v178
	v_exp_f32_e32 v179, v179
	v_exp_f32_e32 v182, v182
	v_exp_f32_e32 v183, v183
	v_cvt_pk_fp8_f32 v138, v235, v236
	v_exp_f32_e32 v172, v172
	v_exp_f32_e32 v173, v173
	v_exp_f32_e32 v176, v176
	v_exp_f32_e32 v177, v177
	v_exp_f32_e32 v184, v184
	v_exp_f32_e32 v185, v185
	v_exp_f32_e32 v180, v180
	v_exp_f32_e32 v181, v181
	v_cvt_pk_fp8_f32 v142, v166, v167
	v_cvt_pk_fp8_f32 v139, v233, v234
	v_cvt_pk_fp8_f32 v143, v174, v175
	v_cvt_pk_fp8_f32 v138, v227, v229 op_sel:[0,0,1]
	v_cvt_pk_fp8_f32 v140, v228, v230
	v_cvt_pk_fp8_f32 v144, v178, v179
	v_cvt_pk_fp8_f32 v141, v225, v226
	v_cvt_pk_fp8_f32 v145, v182, v183
	v_cvt_pk_fp8_f32 v142, v172, v173 op_sel:[0,0,1]
	v_cvt_pk_fp8_f32 v139, v231, v232 op_sel:[0,0,1]
	v_cvt_pk_fp8_f32 v143, v176, v177 op_sel:[0,0,1]
	v_cvt_pk_fp8_f32 v140, v221, v222 op_sel:[0,0,1]
	v_cvt_pk_fp8_f32 v144, v184, v185 op_sel:[0,0,1]
	v_cvt_pk_fp8_f32 v141, v223, v224 op_sel:[0,0,1]
	v_cvt_pk_fp8_f32 v145, v180, v181 op_sel:[0,0,1]
	ds_read_b128 v[172:175], v215 offset:16384
	ds_read_b128 v[222:225], v215 offset:18432
	ds_read_b128 v[176:179], v216 offset:16384
	ds_read_b128 v[226:229], v216 offset:18432
	ds_read_b128 v[230:233], v215 offset:20480
	ds_read_b128 v[238:241], v215 offset:22528
	ds_read_b128 v[234:237], v216 offset:20480
	ds_read_b128 v[242:245], v216 offset:22528
	s_waitcnt lgkmcnt(5)
	v_mfma_f32_32x32x64_f8f6f4 v[48:63], v[138:145], v[172:179], v[48:63]
	s_waitcnt lgkmcnt(4)
	v_mfma_f32_32x32x64_f8f6f4 v[32:47], v[138:145], v[222:229], v[32:47]
	s_waitcnt lgkmcnt(1)
	v_mfma_f32_32x32x64_f8f6f4 v[16:31], v[138:145], v[230:237], v[16:31]
	s_waitcnt lgkmcnt(0)
	v_mfma_f32_32x32x64_f8f6f4 v[0:15], v[138:145], v[238:245], v[0:15]
	v_mfma_f32_32x32x64_f8f6f4 v[64:79], v[138:145], v[114:121], v[64:79]
	v_max_f32_e32 v138, v97, v97
	v_max_f32_e32 v139, v96, v96
	v_max_f32_e32 v138, v139, v138
	v_max3_f32 v138, v138, v98, v99
	v_max3_f32 v138, v138, v100, v101
	v_max3_f32 v138, v138, v102, v103
	v_max3_f32 v138, v138, v104, v105
	v_max3_f32 v138, v138, v106, v107
	v_max3_f32 v138, v138, v108, v109
	v_max3_f32 v138, v138, v110, v111
	v_max3_f32 v138, v138, v80, v81
	v_max3_f32 v138, v138, v82, v83
	v_max3_f32 v138, v138, v84, v85
	v_max3_f32 v138, v138, v86, v87
	v_max3_f32 v138, v138, v88, v89
	v_max3_f32 v138, v138, v90, v91
	v_max3_f32 v138, v138, v92, v93
	v_max3_f32 v138, v138, v94, v95
	v_mov_b32_e32 v139, v138
	s_nop 1
	v_permlane32_swap_b32_e32 v138, v139
	v_max_f32_e32 v139, v139, v139
	v_max_f32_e32 v138, v138, v138
	v_max_f32_e32 v138, v138, v139
	v_sub_f32_e32 v139, v138, v219
	v_cmp_ge_f32_e32 vcc, s63, v139
	s_cmp_lg_u64 vcc, exec
	s_cselect_b64 s[8:9], -1, 0
	s_mov_b64 vcc, s[8:9]
	s_cbranch_vccnz .LBB0_215
	v_mov_b32_e32 v138, v220
